# mode-B rel-pos-bias LDS reads batched (16 in flight instead of read-wait-add x16) on top of previous epilogue load batching
# speedup vs baseline: 1.0063x; 1.0063x over previous
; #define LGKM0() asm volatile("s_waitcnt lgkmcnt(0)" ::: "memory")
; template <int DQK, int DV, int MODE>
; __device__ __forceinline__ void attn_item(LAS unsigned char* lds, int item, const AttnCtx& cx) {
;     ...
;     auto gload = [&](int j) {
; #pragma unroll
;     ...
;     auto do_qk = [&](int j, bool vpre) {
;         const unsigned kaddr = (unsigned)(size_t)(lds + (j % NST) * SB + koff) + r * KP + 16 * h;
;         const unsigned va = vaddr_of(j);
;         bf16x8 kfr[1][4];
;         K_ISSUE(0, 0);
; #pragma unroll
;         for (int kb = 0; kb < NQF / 2; ++kb) {
;             LGKM0(); SBAR();
;             if (kb == 0) { if (MODE == 1) { s0 = MFMA32(kfr[0][0], qf[0], cin0); s1 = MFMA32(kfr[0][1], qf[0], cin1); } else { s0 = MFMA32(kfr[0][0], qf[0], negm); s1 = MFMA32(kfr[0][1], qf[0], negm); } }
;             else { s0 = MFMA32(kfr[0][0], qf[2 * kb], s0); s1 = MFMA32(kfr[0][1], qf[2 * kb], s1); }
;             s0 = MFMA32(kfr[0][2], qf[2 * kb + 1], s0); s1 = MFMA32(kfr[0][3], qf[2 * kb + 1], s1);
;             SBAR();
;             if (kb + 1 < NQF / 2) K_ISSUE(0, kb + 1); else if (vpre) V_ISSUE(va, 0, 0);
;         }
;     };
;     auto do_soft = [&](int j) {
;         if (MODE == 1) {
;             const int rk = na_rs0 + j; const int bbase = (rk - na_rq + 7) * 31 + 15 - na_cq + 64;
; #pragma unroll
;             for (int i = 0; i < 16; ++i) { s0[i] += biasL[bbase + crow(i, h)]; s1[i] += biasL[bbase + crow(i, h) + 32]; }
;         }
;         if (MODE == 2) {
;             const int lk0 = c_l0 - 64 + 64 * j;
; #pragma unroll
;             for (int i = 0; i < 16; ++i) {
;                 const int lka = lk0 + crow(i, h), lkb = lka + 32;
;                 const bool v0 = (lka >= 0) && (lka < c_L) && (abs(lka - c_lq) <= 64), v1 = (lkb >= 0) && (lkb < c_L) && (abs(lkb - c_lq) <= 64);
;                 s0[i] = v0 ? s0[i] : NEGBIG; s1[i] = v1 ? s1[i] : NEGBIG;
;             }
;         }
;         float mx = max3f(s0[0], s1[0], s0[1]);
;         mx = max3f(mx, s1[1], s0[2]);
; #pragma unroll
;         for (int i = 2; i < 15; ++i) mx = max3f(mx, s1[i], s0[i + 1]);
;         mx = fmaxf(mx, s1[15]);
;         { auto rr = __builtin_amdgcn_permlane32_swap(__float_as_uint(mx), __float_as_uint(mx), false, false); mx = max3f(__uint_as_float(rr[0]), __uint_as_float(rr[1]), __uint_as_float(rr[0])); }
;         if (first || __builtin_amdgcn_ballot_w64(mx > THR) != 0ull) {
.LBB0_332:
	s_add_i32 s40, s51, s22
	s_add_i32 s0, s40, 1
	s_min_i32 s0, s0, s36
	s_lshl_b32 s41, s0, 6
	v_add_u32_e32 v116, s41, v199
	v_mov_b64_e32 v[114:115], s[86:87]
	v_mad_i64_i32 v[116:117], s[0:1], v116, s33, v[114:115]
	v_add_u32_e32 v120, s41, v200
	v_lshl_add_u64 v[118:119], v[116:117], 0, s[96:97]
	v_mad_i64_i32 v[114:115], s[0:1], v120, s33, v[114:115]
	v_lshl_add_u64 v[116:117], v[116:117], 0, s[94:95]
	v_lshl_add_u64 v[118:119], v[118:119], 0, v[0:1]
	v_lshl_add_u64 v[120:121], v[114:115], 0, s[96:97]
	v_lshl_add_u64 v[116:117], v[116:117], 0, v[0:1]
	v_lshl_add_u64 v[114:115], v[114:115], 0, s[94:95]
	v_lshl_add_u64 v[120:121], v[120:121], 0, v[0:1]
	global_load_dwordx4 v[162:165], v[118:119], off
	global_load_dwordx4 v[166:169], v[120:121], off
	v_lshl_add_u64 v[114:115], v[114:115], 0, v[0:1]
	global_load_dwordx4 v[170:173], v[116:117], off
	global_load_dwordx4 v[174:177], v[114:115], off
	s_cmp_ge_u32 s40, s37
	s_cselect_b64 s[0:1], -1, 0
	s_cmp_lt_u32 s40, s42
	s_cselect_b64 s[40:41], -1, 0
	s_and_b64 s[0:1], s[0:1], s[40:41]
	s_andn2_b64 vcc, exec, s[0:1]
	s_cbranch_vccnz .LBB0_331
	s_xor_b64 s[40:41], s[38:39], -1
	s_bitcmp1_b32 s22, 0
	s_cselect_b32 s0, 0xa800, 0
	s_add_i32 s0, s23, s0
	v_add_u32_e32 v211, s0, v204
	ds_read_b128 v[114:117], v211 offset:0
	ds_read_b128 v[178:181], v211 offset:4608
	ds_read_b128 v[182:185], v211 offset:32
	ds_read_b128 v[186:189], v211 offset:4640
	s_waitcnt lgkmcnt(0)
	s_addk_i32 s0, 0x2400
	v_add_u32_e32 v210, s0, v207
	v_mfma_f32_32x32x16_bf16 v[130:145], v[114:117], v[158:161], v[98:113]
	v_mfma_f32_32x32x16_bf16 v[114:129], v[178:181], v[158:161], v[82:97]
	v_mfma_f32_32x32x16_bf16 v[130:145], v[182:185], v[154:157], v[130:145]
	v_mfma_f32_32x32x16_bf16 v[114:129], v[186:189], v[154:157], v[114:129]
	ds_read_b128 v[178:181], v211 offset:64
	ds_read_b128 v[182:185], v211 offset:4672
	ds_read_b128 v[186:189], v211 offset:96
	ds_read_b128 v[190:193], v211 offset:4704
	s_waitcnt lgkmcnt(0)
	s_nop 0
	v_mfma_f32_32x32x16_bf16 v[130:145], v[178:181], v[150:153], v[130:145]
	v_mfma_f32_32x32x16_bf16 v[114:129], v[182:185], v[150:153], v[114:129]
	v_mfma_f32_32x32x16_bf16 v[130:145], v[186:189], v[146:149], v[130:145]
	v_mfma_f32_32x32x16_bf16 v[114:129], v[190:193], v[146:149], v[114:129]
	ds_read_b64_tr_b16 v[190:191], v210 offset:0
	ds_read_b64_tr_b16 v[192:193], v210 offset:1536
	ds_read_b64_tr_b16 v[186:187], v210 offset:3072
	ds_read_b64_tr_b16 v[188:189], v210 offset:4608
	ds_read_b64_tr_b16 v[182:183], v210 offset:6144
	ds_read_b64_tr_b16 v[184:185], v210 offset:7680
	ds_read_b64_tr_b16 v[178:179], v210 offset:9216
	v_add_u32_e32 v211, s43, v208
	ds_read_b64_tr_b16 v[180:181], v210 offset:10752
	v_add_u32_e32 v214, 0x15880, v211
	ds_read2_b32 v[222:223], v214 offset0:0 offset1:1
	ds_read2_b32 v[224:225], v214 offset0:32 offset1:33
	ds_read2_b32 v[226:227], v214 offset0:2 offset1:3
	ds_read2_b32 v[228:229], v214 offset0:34 offset1:35
	ds_read2_b32 v[230:231], v214 offset0:8 offset1:9
	ds_read2_b32 v[232:233], v214 offset0:40 offset1:41
	ds_read2_b32 v[234:235], v214 offset0:10 offset1:11
	ds_read2_b32 v[236:237], v214 offset0:42 offset1:43
	ds_read2_b32 v[238:239], v214 offset0:16 offset1:17
	ds_read2_b32 v[240:241], v214 offset0:48 offset1:49
	ds_read2_b32 v[242:243], v214 offset0:18 offset1:19
	ds_read2_b32 v[244:245], v214 offset0:50 offset1:51
	ds_read2_b32 v[246:247], v214 offset0:24 offset1:25
	ds_read2_b32 v[248:249], v214 offset0:56 offset1:57
	ds_read2_b32 v[212:213], v214 offset0:26 offset1:27
	ds_read2_b32 v[216:217], v214 offset0:58 offset1:59
	s_andn2_b64 vcc, exec, s[40:41]
	s_waitcnt lgkmcnt(0)
	s_nop 4
	v_pk_add_f32 v[130:131], v[130:131], v[222:223]
	v_pk_add_f32 v[114:115], v[114:115], v[224:225]
	v_pk_add_f32 v[132:133], v[132:133], v[226:227]
	v_pk_add_f32 v[116:117], v[116:117], v[228:229]
	v_pk_add_f32 v[134:135], v[134:135], v[230:231]
	v_pk_add_f32 v[118:119], v[118:119], v[232:233]
	v_pk_add_f32 v[136:137], v[136:137], v[234:235]
	v_pk_add_f32 v[120:121], v[120:121], v[236:237]
	v_pk_add_f32 v[138:139], v[138:139], v[238:239]
	v_pk_add_f32 v[122:123], v[122:123], v[240:241]
	v_pk_add_f32 v[140:141], v[140:141], v[242:243]
	v_pk_add_f32 v[124:125], v[124:125], v[244:245]
	v_pk_add_f32 v[142:143], v[142:143], v[246:247]
	v_pk_add_f32 v[126:127], v[126:127], v[248:249]
	v_pk_add_f32 v[144:145], v[144:145], v[212:213]
	v_pk_add_f32 v[128:129], v[128:129], v[216:217]
	v_max3_f32 v211, v130, v114, v131
	v_max3_f32 v211, v211, v115, v132
	s_nop 0
	v_max3_f32 v211, v211, v116, v133
	s_nop 0
	v_max3_f32 v211, v211, v117, v134
	s_nop 0
	v_max3_f32 v211, v211, v118, v135
	s_nop 0
	v_max3_f32 v211, v211, v119, v136
	s_nop 0
	v_max3_f32 v211, v211, v120, v137
	s_nop 0
	v_max3_f32 v211, v211, v121, v138
	s_nop 0
	v_max3_f32 v211, v211, v122, v139
	s_nop 0
	v_max3_f32 v211, v211, v123, v140
	s_nop 0
	v_max3_f32 v211, v211, v124, v141
	s_nop 0
	v_max3_f32 v211, v211, v125, v142
	s_nop 0
	v_max3_f32 v211, v211, v126, v143
	s_nop 0
	v_max3_f32 v211, v211, v127, v144
	s_nop 0
	v_max3_f32 v211, v211, v128, v145
	s_nop 0
	v_max_f32_e32 v211, v211, v211
	v_max_f32_e32 v211, v211, v129
	v_mov_b32_e32 v212, v211
	s_nop 1
	v_permlane32_swap_b32_e32 v211, v212
	v_max3_f32 v211, v211, v212, v211
	v_cndmask_b32_e64 v212, 0, 1, s[40:41]
	v_cmp_ne_u32_e64 s[0:1], 1, v212
	s_mov_b64 s[40:41], s[38:39]
	s_cbranch_vccnz .LBB0_335
	v_cmp_lt_f32_e32 vcc, s29, v211
	s_cmp_lg_u64 vcc, 0
	s_cselect_b64 s[40:41], -1, 0
